# phase 3: weight-conversion waves sleep ~1.5k cycles per item so the HBM queue is shorter for the latency-bound scan workgroups
# speedup vs baseline: 1.0070x; 1.0070x over previous
; DI void convert_weights(const Args& a, int l, int sets, bf16_t* dstWin, int gw, int NGW, LAS unsigned char* lds, const int tidx) {
;     ...
;         for (int it = gw; it < I_OUT + I_UP + I_DN; it += NGW) {
;             int r = it;
;             if (r < I_OUT) { const int nblk = DM / 32, kb = r / nblk, nb = r % nblk; transpose_item(wout, DM, DM, 32 * nb, 32, nullptr, WoutT, 32 * nb, 64 * kb, scr, lane); continue; } r -= I_OUT;
;             if (r < I_UP) { const int nblk = DFF / 32, kb = r / nblk, nb = r % nblk; transpose_item(wup, DM, DFF, 32 * nb, 32, a.norm2_w + l * DM, WupT, 32 * nb, 64 * kb, scr, lane); continue; } r -= I_UP;
;             { const int nblk = DM / 32, kb = r / nblk, nb = r % nblk; transpose_item(wdn, DFF, DM, 32 * nb, 32, nullptr, WdnT, 32 * nb, 64 * kb, scr, lane); }
;         }
.LBB0_268:
	s_sleep 24
	s_or_b64 exec, exec, s[0:1]
	v_readlane_b32 s0, v252, 13
	v_add_u32_e32 v52, s14, v52
	s_nop 0
	v_add_u32_e32 v44, s0, v44
	s_movk_i32 s0, 0x47ff
	v_cmp_lt_i32_e32 vcc, s0, v44
	s_or_b64 s[8:9], vcc, s[8:9]
	s_andn2_b64 exec, exec, s[8:9]
	s_cbranch_execz .LBB0_293

; #define LAS __attribute__((address_space(3)))
; DI unsigned pk2(float lo, float hi) { const f32x2_t v = {lo, hi}; return __builtin_bit_cast(unsigned, __builtin_convertvector(v, bf16x2_t)); }
; DI void transpose_item(const float* W, int K, int Nsrc, int srccol, int nvalid, const float* ksc, bf16_t* WT, int dstrow, int k0, LAS float* scr, int lane) {
;     ...
; #pragma unroll
;     for (int i = 0; i < 8; ++i) { LAS float* d = scr + (8 * i + (lane >> 3)) * 33 + 4 * (lane & 7); d[0] = v[i].x; d[1] = v[i].y; d[2] = v[i].z; d[3] = v[i].w; }
;     asm volatile("s_waitcnt lgkmcnt(0)" ::: "memory");
;     const int c = lane & 7;
; #pragma unroll
;     for (int j = 0; j < 4; ++j) { const int n = (lane >> 3) + 8 * j; const LAS float* s = scr + (8 * c) * 33 + n;
;         u32x4 o; o.x = pk2(s[0 * 33], s[1 * 33]); o.y = pk2(s[2 * 33], s[3 * 33]); o.z = pk2(s[4 * 33], s[5 * 33]); o.w = pk2(s[6 * 33], s[7 * 33]);
;         *(u32x4*)(WT + (size_t)(dstrow + n) * K + k0 + 8 * c) = o; }
;     asm volatile("s_waitcnt lgkmcnt(0)" ::: "memory");
; }
; DI void convert_weights(const Args& a, int l, int sets, bf16_t* dstWin, int gw, int NGW, LAS unsigned char* lds, const int tidx) {
;     ...
;         for (int r = gw; r < I_IN; r += NGW) { const int nblk = NPAD / 32, kb = r / nblk, nb = r % nblk; const int dn = 32 * nb, nv = dn < 6912 ? 32 : (dn == 6912 ? 12 : 0);
;             transpose_item(win, DM, INDIM, win_srccol(dn < 6924 ? dn : 0), nv, a.norm1_w + l * DM, dstWin, dn, 64 * kb, scr, lane); }
.LBB0_297:
	s_sleep 24
	s_waitcnt vmcnt(0)
	ds_write2_b32 v46, v0, v1 offset1:1
	ds_write2_b32 v46, v2, v3 offset0:2 offset1:3
	v_add_u32_e32 v0, 0x420, v46
	ds_write2_b32 v0, v4, v5 offset1:1
	v_add_u32_e32 v0, 0x428, v46
	ds_write2_b32 v0, v6, v7 offset1:1
	v_add_u32_e32 v0, 0x840, v46
	ds_write2_b32 v0, v8, v9 offset1:1
	v_add_u32_e32 v0, 0x848, v46
	ds_write2_b32 v0, v10, v11 offset1:1
	v_add_u32_e32 v0, 0xc60, v46
	ds_write2_b32 v0, v12, v13 offset1:1
	v_add_u32_e32 v0, 0xc68, v46
	ds_write2_b32 v0, v14, v15 offset1:1
	v_add_u32_e32 v0, 0x1080, v46
	ds_write2_b32 v0, v16, v17 offset1:1
	v_add_u32_e32 v0, 0x1088, v46
	ds_write2_b32 v0, v18, v19 offset1:1
	v_add_u32_e32 v0, 0x14a0, v46
	ds_write2_b32 v0, v20, v21 offset1:1
	v_add_u32_e32 v0, 0x14a8, v46
	ds_write2_b32 v0, v22, v23 offset1:1
	v_add_u32_e32 v0, 0x18c0, v46
	ds_write2_b32 v0, v24, v25 offset1:1
	v_add_u32_e32 v0, 0x18c8, v46
	ds_write2_b32 v0, v26, v27 offset1:1
	v_add_u32_e32 v0, 0x1ce0, v46
	ds_write2_b32 v0, v28, v29 offset1:1
	v_add_u32_e32 v0, 0x1ce8, v46
	ds_write2_b32 v0, v30, v31 offset1:1
	s_waitcnt lgkmcnt(0)
	ds_read2_b32 v[4:5], v44 offset0:33 offset1:41
	ds_read2_b32 v[6:7], v44 offset1:8
	ds_read2_b32 v[8:9], v44 offset0:66 offset1:74
	ds_read2_b32 v[10:11], v44 offset0:99 offset1:107
	ds_read2_b32 v[12:13], v44 offset0:132 offset1:140
	ds_read2_b32 v[14:15], v44 offset0:165 offset1:173
	ds_read2_b32 v[16:17], v44 offset0:198 offset1:206
	ds_read2_b32 v[18:19], v44 offset0:231 offset1:239
	v_add3_u32 v22, v33, v45, v47
	v_ashrrev_i32_e32 v39, 31, v38
	v_ashrrev_i32_e32 v23, 31, v22
	v_lshl_add_u64 v[20:21], v[38:39], 1, v[36:37]
	v_lshlrev_b64 v[24:25], 12, v[22:23]
	s_waitcnt lgkmcnt(6)
	v_cvt_pk_bf16_f32 v0, v6, v4
	s_waitcnt lgkmcnt(4)
	v_cvt_pk_bf16_f32 v1, v8, v10
	s_waitcnt lgkmcnt(2)
	v_cvt_pk_bf16_f32 v2, v12, v14
	s_waitcnt lgkmcnt(0)
	v_cvt_pk_bf16_f32 v3, v16, v18
	v_lshl_add_u64 v[24:25], v[20:21], 0, v[24:25]
	v_add_u32_e32 v4, 8, v22
	global_store_dwordx4 v[24:25], v[0:3], off
	v_readlane_b32 s4, v252, 13
	v_add_u32_e32 v45, s22, v45
	v_cvt_pk_bf16_f32 v0, v7, v5
	v_ashrrev_i32_e32 v5, 31, v4
	v_cvt_pk_bf16_f32 v1, v9, v11
	v_cvt_pk_bf16_f32 v2, v13, v15
	v_cvt_pk_bf16_f32 v3, v17, v19
	v_lshlrev_b64 v[4:5], 12, v[4:5]
	ds_read2_b32 v[6:7], v44 offset0:49 offset1:57
	ds_read2_b32 v[8:9], v44 offset0:16 offset1:24
	ds_read2_b32 v[10:11], v44 offset0:82 offset1:90
	ds_read2_b32 v[12:13], v44 offset0:115 offset1:123
	ds_read2_b32 v[14:15], v44 offset0:148 offset1:156
	ds_read2_b32 v[16:17], v44 offset0:181 offset1:189
	ds_read2_b32 v[18:19], v44 offset0:214 offset1:222
	ds_read2_b32 v[24:25], v44 offset0:247 offset1:255
	v_lshl_add_u64 v[4:5], v[20:21], 0, v[4:5]
	global_store_dwordx4 v[4:5], v[0:3], off
	v_add_u32_e32 v4, 16, v22
	v_ashrrev_i32_e32 v5, 31, v4
	v_lshlrev_b64 v[4:5], 12, v[4:5]
	s_waitcnt lgkmcnt(6)
	v_cvt_pk_bf16_f32 v0, v8, v6
	s_waitcnt lgkmcnt(4)
	v_cvt_pk_bf16_f32 v1, v10, v12
	s_waitcnt lgkmcnt(2)
	v_cvt_pk_bf16_f32 v2, v14, v16
	s_waitcnt lgkmcnt(0)
	v_cvt_pk_bf16_f32 v3, v18, v24
	v_lshl_add_u64 v[4:5], v[20:21], 0, v[4:5]
	global_store_dwordx4 v[4:5], v[0:3], off
	v_add_u32_e32 v4, 24, v22
	v_ashrrev_i32_e32 v5, 31, v4
	v_lshlrev_b64 v[4:5], 12, v[4:5]
	v_cvt_pk_bf16_f32 v0, v9, v7
	v_cvt_pk_bf16_f32 v1, v11, v13
	v_cvt_pk_bf16_f32 v2, v15, v17
	v_cvt_pk_bf16_f32 v3, v19, v25
	v_lshl_add_u64 v[4:5], v[20:21], 0, v[4:5]
	global_store_dwordx4 v[4:5], v[0:3], off
	s_waitcnt lgkmcnt(0)
	v_add_u32_e32 v32, s4, v32
	s_movk_i32 s4, 0x1bff
	v_cmp_lt_i32_e32 vcc, s4, v32
	s_or_b64 s[8:9], vcc, s[8:9]
	s_andn2_b64 exec, exec, s[8:9]
	s_cbranch_execz .LBB0_356
